# HGRN2 mixer: exp2(b_ref) table computed once per chunk, St image written after SYNC2
# baseline (speedup 1.0000x reference)
; template <int DK, bool IS_A, int NDV>
; __device__ __forceinline__ void mix_stream(const Params& p, LAS unsigned char* lds, int l, int rs, int T, int h, int dir, int dvh) {
;     ...
;         for (int dki = 0; dki < 2; ++dki) { f32x4 er;
;           if (IS_A) { const int dk = (tdk0 + dki) * 16 + fq * 4; const f32x4 e = *(const LAS f32x4*)(seg + dk) + *(const LAS f32x4*)(seg + DK + dk) + *(const LAS f32x4*)(seg + 2 * DK + dk) + *(const LAS f32x4*)(seg + 3 * DK + dk);
; #pragma unroll
;               for (int j = 0; j < 4; ++j) er[j] = exp2_(fmaxf(e[j], -115.f)); }
;           else { const float e = __expf(32.0f * lg); er = (f32x4){e, e, e, e}; }
; #pragma unroll
;           for (int dvi = 0; dvi < DVW; ++dvi) { const f32x4 sv = S[dki * DVW + dvi] * er; u32x2 pk; pk.x = cvt_pk_bf16(sv[0], sv[1]); pk.y = cvt_pk_bf16(sv[2], sv[3]);
;               *(LAS u32x2*)(St + ((tdv0 + dvi) * 16 + fr) * QP + ((((tdk0 + dki) * 16 + fq * 4) * 2) ^ (gx << 4))) = pk; } }
;     ...
;         { const int tt = w >> 1, ts0 = (w & 1) * 2; f32x4 pa = (f32x4){0.f, 0.f, 0.f, 0.f}, pb = pa;
;           bf16x8 gq_[KS], gk0[KS], gk1[KS];
; #pragma unroll
;           for (int ks = 0; ks < KS; ++ks) { gq_[ks] = ldfrag(Qs, QP, tt, ks, fr, fqx); gk0[ks] = ldfrag(Ks, QP, ts0, ks, fr, fqx); gk1[ks] = ldfrag(Ks, QP, ts0 + 1, ks, fr, fqx); }
;           __builtin_amdgcn_sched_barrier(0);
; #pragma unroll
;           for (int ks = 0; ks < KS; ++ks) { pa = MFMA16(gk0[ks], gq_[ks], pa); pb = MFMA16(gk1[ks], gq_[ks], pb); }
;           const int t = tt * 16 + fr, s0 = ts0 * 16 + fq * 4, s1 = s0 + 16;
;           u32x2 w0, w1;
;           w0.x = cvt_pk_bf16(t >= s0 ? pa[0] : 0.f, t >= s0 + 1 ? pa[1] : 0.f); w0.y = cvt_pk_bf16(t >= s0 + 2 ? pa[2] : 0.f, t >= s0 + 3 ? pa[3] : 0.f);
;           w1.x = cvt_pk_bf16(t >= s1 ? pb[0] : 0.f, t >= s1 + 1 ? pb[1] : 0.f); w1.y = cvt_pk_bf16(t >= s1 + 2 ? pb[2] : 0.f, t >= s1 + 3 ? pb[3] : 0.f);
;           *(LAS u32x2*)(Ps + t * TP + ((s0 * 2) ^ (gx << 4))) = w0; *(LAS u32x2*)(Ps + t * TP + ((s1 * 2) ^ (gx << 4))) = w1; }
; #pragma unroll
;         for (int ks = 0; ks < 2; ++ks) { bf16x8 ak[2], bv[DVW];
; #pragma unroll
;             for (int dki = 0; dki < 2; ++dki) ak[dki] = ldfrag(Kt, TP, tdk0 + dki, ks, fr, fqx);
; #pragma unroll
;             for (int dvi = 0; dvi < DVW; ++dvi) bv[dvi] = ldfrag(Vt, TP, tdv0 + dvi, ks, fr, fqx);
.LBB0_172:
	s_waitcnt lgkmcnt(0)
	s_barrier
	ds_read_b128 v[0:3], v130 offset:18432
	ds_read_b128 v[90:93], v130 offset:18496
	s_waitcnt lgkmcnt(1)
	v_pk_mul_f32 v[6:7], v[56:57], v[0:1]
	s_nop 0
	v_cvt_pk_bf16_f32 v6, v6, v7
	v_pk_mul_f32 v[4:5], v[58:59], v[2:3]
	s_nop 0
	v_cvt_pk_bf16_f32 v7, v4, v5
	ds_write_b64 v135, v[6:7]
	v_pk_mul_f32 v[6:7], v[60:61], v[0:1]
	v_pk_mul_f32 v[4:5], v[62:63], v[2:3]
	v_cvt_pk_bf16_f32 v6, v6, v7
	s_nop 0
	v_cvt_pk_bf16_f32 v7, v4, v5
	ds_write_b64 v135, v[6:7] offset:4352
	v_pk_mul_f32 v[6:7], v[64:65], v[0:1]
	v_pk_mul_f32 v[0:1], v[68:69], v[0:1]
	v_pk_mul_f32 v[4:5], v[66:67], v[2:3]
	v_cvt_pk_bf16_f32 v6, v6, v7
	v_pk_mul_f32 v[2:3], v[70:71], v[2:3]
	v_cvt_pk_bf16_f32 v7, v4, v5
	ds_write_b64 v135, v[6:7] offset:8704
	v_cvt_pk_bf16_f32 v0, v0, v1
	v_cvt_pk_bf16_f32 v1, v2, v3
	ds_write_b64 v135, v[0:1] offset:13056
	s_waitcnt lgkmcnt(4)
	v_pk_mul_f32 v[6:7], v[72:73], v[90:91]
	s_nop 0
	v_cvt_pk_bf16_f32 v6, v6, v7
	v_pk_mul_f32 v[4:5], v[74:75], v[92:93]
	s_nop 0
	v_cvt_pk_bf16_f32 v7, v4, v5
	ds_write_b64 v136, v[6:7]
	v_pk_mul_f32 v[6:7], v[76:77], v[90:91]
	v_pk_mul_f32 v[4:5], v[78:79], v[92:93]
	v_cvt_pk_bf16_f32 v6, v6, v7
	s_nop 0
	v_cvt_pk_bf16_f32 v7, v4, v5
	ds_write_b64 v136, v[6:7] offset:4352
	v_pk_mul_f32 v[6:7], v[80:81], v[90:91]
	v_pk_mul_f32 v[0:1], v[84:85], v[90:91]
	v_pk_mul_f32 v[4:5], v[82:83], v[92:93]
	v_cvt_pk_bf16_f32 v6, v6, v7
	v_pk_mul_f32 v[2:3], v[86:87], v[92:93]
	v_cvt_pk_bf16_f32 v7, v4, v5
	ds_write_b64 v136, v[6:7] offset:8704
	v_cvt_pk_bf16_f32 v0, v0, v1
	v_cvt_pk_bf16_f32 v1, v2, v3
	ds_write_b64 v136, v[0:1] offset:13056
	s_waitcnt lgkmcnt(3)
	ds_read_b128 v[0:3], v137
	ds_read_b128 v[4:7], v137 offset:64
	ds_read_b128 v[90:93], v138 offset:17408
	ds_read_b128 v[94:97], v138 offset:17472
	ds_read_b128 v[98:101], v139 offset:17408
	ds_read_b128 v[102:105], v139 offset:17472
	ds_read_b128 v[166:169], v137 offset:128
	ds_read_b128 v[170:173], v137 offset:192
	ds_read_b128 v[180:183], v138 offset:17536
	ds_read_b128 v[184:187], v138 offset:17600
	ds_read_b128 v[188:191], v139 offset:17536
	ds_read_b128 v[192:195], v139 offset:17600
	s_waitcnt lgkmcnt(9)
	v_mfma_f32_16x16x32_bf16 v[90:93], v[90:93], v[0:3], 0
	s_waitcnt lgkmcnt(7)
	v_mfma_f32_16x16x32_bf16 v[0:3], v[98:101], v[0:3], 0
	v_mfma_f32_16x16x32_bf16 v[90:93], v[94:97], v[4:7], v[90:93]
	s_waitcnt lgkmcnt(6)
	v_mfma_f32_16x16x32_bf16 v[0:3], v[102:105], v[4:7], v[0:3]
	s_waitcnt lgkmcnt(3)
	v_mfma_f32_16x16x32_bf16 v[4:7], v[180:183], v[166:169], v[90:93]
	s_waitcnt lgkmcnt(1)
	v_mfma_f32_16x16x32_bf16 v[0:3], v[188:191], v[166:169], v[0:3]
	v_mfma_f32_16x16x32_bf16 v[4:7], v[184:187], v[170:173], v[4:7]
	s_waitcnt lgkmcnt(0)
	v_mfma_f32_16x16x32_bf16 v[0:3], v[192:195], v[170:173], v[0:3]
	s_nop 5
	v_cndmask_b32_e64 v4, v4, 0, s[42:43]
	v_cndmask_b32_e64 v5, 0, v5, s[44:45]
	v_cvt_pk_bf16_f32 v4, v4, v5
	v_cndmask_b32_e64 v5, v6, 0, s[46:47]
	v_cndmask_b32_e64 v0, v0, 0, s[50:51]
	v_cndmask_b32_e64 v1, v1, 0, s[52:53]
	v_cndmask_b32_e64 v6, v7, 0, s[48:49]
	v_cvt_pk_bf16_f32 v5, v5, v6
	v_cvt_pk_bf16_f32 v0, v0, v1
	v_cndmask_b32_e64 v1, v2, 0, s[54:55]
	v_cndmask_b32_e64 v2, v3, 0, s[56:57]
	v_cvt_pk_bf16_f32 v1, v1, v2
	ds_write_b64 v140, v[4:5]
	ds_write_b64 v141, v[0:1]
	ds_read_b128 v[0:3], v142 offset:53248
	ds_read_b128 v[4:7], v143 offset:53248
	ds_read_b128 v[90:93], v144 offset:34816
	ds_read_b128 v[94:97], v144 offset:37120
	ds_read_b128 v[98:101], v144 offset:39424
	ds_read_b128 v[102:105], v144 offset:41728
	s_waitcnt lgkmcnt(3)
	v_mfma_f32_16x16x32_bf16 v[166:169], v[0:3], v[90:93], 0
	s_waitcnt lgkmcnt(2)
	v_mfma_f32_16x16x32_bf16 v[170:173], v[0:3], v[94:97], 0
	s_waitcnt lgkmcnt(1)
	v_mfma_f32_16x16x32_bf16 v[180:183], v[0:3], v[98:101], 0
	s_waitcnt lgkmcnt(0)
	v_mfma_f32_16x16x32_bf16 v[0:3], v[0:3], v[102:105], 0
	v_mfma_f32_16x16x32_bf16 v[90:93], v[4:7], v[90:93], 0
	v_mfma_f32_16x16x32_bf16 v[94:97], v[4:7], v[94:97], 0
	v_mfma_f32_16x16x32_bf16 v[98:101], v[4:7], v[98:101], 0
	v_mfma_f32_16x16x32_bf16 v[4:7], v[4:7], v[102:105], 0
	ds_read_b128 v[102:105], v142 offset:53312
	ds_read_b128 v[184:187], v143 offset:53312
	ds_read_b128 v[188:191], v144 offset:34880
	ds_read_b128 v[192:195], v144 offset:37184
	ds_read_b128 v[196:199], v144 offset:39488
	ds_read_b128 v[200:203], v144 offset:41792
	s_waitcnt lgkmcnt(3)
	v_mfma_f32_16x16x32_bf16 v[166:169], v[102:105], v[188:191], v[166:169]
	s_waitcnt lgkmcnt(2)
	v_mfma_f32_16x16x32_bf16 v[170:173], v[102:105], v[192:195], v[170:173]
	s_waitcnt lgkmcnt(1)
	v_mfma_f32_16x16x32_bf16 v[180:183], v[102:105], v[196:199], v[180:183]
	s_waitcnt lgkmcnt(0)
	v_mfma_f32_16x16x32_bf16 v[0:3], v[102:105], v[200:203], v[0:3]
	v_mfma_f32_16x16x32_bf16 v[90:93], v[184:187], v[188:191], v[90:93]
	v_mfma_f32_16x16x32_bf16 v[94:97], v[184:187], v[192:195], v[94:97]
	v_mfma_f32_16x16x32_bf16 v[98:101], v[184:187], v[196:199], v[98:101]
	v_mfma_f32_16x16x32_bf16 v[4:7], v[184:187], v[200:203], v[4:7]
	s_waitcnt lgkmcnt(0)
	s_barrier
; #define LAS __attribute__((address_space(3)))
; template <int DK, bool IS_A, int NDV>
; __device__ __forceinline__ void mix_stream(const Params& p, LAS unsigned char* lds, int l, int rs, int T, int h, int dir, int dvh) {
;     ...
;         { const int tp = w >> 2, dp = w & 3; f32x4 o[4];
; #pragma unroll
;           for (int q = 0; q < 4; ++q) o[q] = (f32x4){0.f, 0.f, 0.f, 0.f};
; #pragma unroll
;           for (int kb = 0; kb < KS; kb += 2) { bf16x8 b[2][2], a[2][2];
; #pragma unroll
;               for (int k2 = 0; k2 < 2; ++k2)
; #pragma unroll
;                   for (int i2 = 0; i2 < 2; ++i2) { b[k2][i2] = ldfrag(Qs, QP, 2 * tp + i2, kb + k2, fr, fqx); a[k2][i2] = ldfrag(St, QP, 2 * dp + i2, kb + k2, fr, fqx); }
;               __builtin_amdgcn_sched_barrier(0);
; #pragma unroll
;               for (int k2 = 0; k2 < 2; ++k2)
; #pragma unroll
;                   for (int ti = 0; ti < 2; ++ti)
; #pragma unroll
;                       for (int di = 0; di < 2; ++di) o[ti * 2 + di] = MFMA16(a[k2][di], b[k2][ti], o[ti * 2 + di]);
;               __builtin_amdgcn_sched_barrier(0); }
;           { bf16x8 b[2][2], a[2][2];
; #pragma unroll
;               for (int k2 = 0; k2 < 2; ++k2)
; #pragma unroll
;                   for (int i2 = 0; i2 < 2; ++i2) { b[k2][i2] = ldfrag(Ps, TP, 2 * tp + i2, k2, fr, fqx); a[k2][i2] = ldfrag(Vt, TP, 2 * dp + i2, k2, fr, fqx); }
;               __builtin_amdgcn_sched_barrier(0);
; #pragma unroll
;               for (int k2 = 0; k2 < 2; ++k2)
; #pragma unroll
;                   for (int ti = 0; ti < 2; ++ti)
; #pragma unroll
;                       for (int di = 0; di < 2; ++di) o[ti * 2 + di] = MFMA16(a[k2][di], b[k2][ti], o[ti * 2 + di]);
;               __builtin_amdgcn_sched_barrier(0); }
; #pragma unroll
;           for (int ti = 0; ti < 2; ++ti)
; #pragma unroll
;               for (int di = 0; di < 2; ++di) { const f32x4 ov = o[ti * 2 + di]; u32x2 pk; pk.x = cvt_pk_bf16(ov[0], ov[1]); pk.y = cvt_pk_bf16(ov[2], ov[3]);
;                   *(LAS u32x2*)(Os + ((2 * tp + ti) * 16 + fr) * OP + ((2 * dp + di) * 16 + fq * 4) * 2) = pk; } }
; #pragma unroll
;         for (int dki = 0; dki < 2; ++dki) { f32x4 cd, cs;
;           if (IS_A) { cd = *(const LAS f32x4*)(cdec + (tdk0 + dki) * 16 + fq * 4); cs = *(const LAS f32x4*)(csc + (tdk0 + dki) * 16 + fq * 4); }
	v_add_u32_e32 v174, v111, v126
	ds_read_b128 v[102:105], v174
	ds_read_b128 v[184:187], v174 offset:64
	ds_read_b128 v[188:191], v145
	ds_read_b128 v[192:195], v145 offset:64
	ds_read_b128 v[196:199], v174 offset:4352
	ds_read_b128 v[200:203], v174 offset:4416
	ds_read_b128 v[204:207], v146
	ds_read_b128 v[208:211], v146 offset:64
	s_waitcnt lgkmcnt(5)
	v_mfma_f32_16x16x32_bf16 v[212:215], v[188:191], v[102:105], 0
	s_waitcnt lgkmcnt(1)
	v_mfma_f32_16x16x32_bf16 v[102:105], v[204:207], v[102:105], 0
	v_mfma_f32_16x16x32_bf16 v[188:191], v[188:191], v[196:199], 0
	v_mfma_f32_16x16x32_bf16 v[196:199], v[204:207], v[196:199], 0
	v_mfma_f32_16x16x32_bf16 v[204:207], v[192:195], v[184:187], v[212:215]
	s_waitcnt lgkmcnt(0)
	v_mfma_f32_16x16x32_bf16 v[102:105], v[208:211], v[184:187], v[102:105]
	v_mfma_f32_16x16x32_bf16 v[184:187], v[192:195], v[200:203], v[188:191]
	v_mfma_f32_16x16x32_bf16 v[188:191], v[208:211], v[200:203], v[196:199]
	ds_read_b128 v[192:195], v174 offset:128
	s_nop 1
	ds_read_b128 v[196:199], v174 offset:192
	ds_read_b128 v[200:203], v145 offset:128
	ds_read_b128 v[208:211], v145 offset:192
	ds_read_b128 v[212:215], v174 offset:4480
	ds_read_b128 v[216:219], v174 offset:4544
	ds_read_b128 v[220:223], v146 offset:128
	ds_read_b128 v[224:227], v146 offset:192
	s_waitcnt lgkmcnt(5)
	v_mfma_f32_16x16x32_bf16 v[204:207], v[200:203], v[192:195], v[204:207]
	s_waitcnt lgkmcnt(1)
	v_mfma_f32_16x16x32_bf16 v[102:105], v[220:223], v[192:195], v[102:105]
	v_mfma_f32_16x16x32_bf16 v[184:187], v[200:203], v[212:215], v[184:187]
	v_mfma_f32_16x16x32_bf16 v[188:191], v[220:223], v[212:215], v[188:191]
	v_mfma_f32_16x16x32_bf16 v[192:195], v[208:211], v[196:199], v[204:207]
	s_waitcnt lgkmcnt(0)
	v_mfma_f32_16x16x32_bf16 v[102:105], v[224:227], v[196:199], v[102:105]
	v_mfma_f32_16x16x32_bf16 v[184:187], v[208:211], v[216:219], v[184:187]
	v_mfma_f32_16x16x32_bf16 v[188:191], v[224:227], v[216:219], v[188:191]
	ds_read_b128 v[196:199], v148
	ds_read_b128 v[200:203], v148 offset:64
	ds_read_b128 v[204:207], v142 offset:34816
	ds_read_b128 v[208:211], v142 offset:34880
	ds_read_b128 v[212:215], v148 offset:2304
	ds_read_b128 v[216:219], v148 offset:2368
	ds_read_b128 v[220:223], v143 offset:34816
	ds_read_b128 v[224:227], v143 offset:34880
	s_waitcnt lgkmcnt(5)
	v_mfma_f32_16x16x32_bf16 v[192:195], v[204:207], v[196:199], v[192:195]
	s_waitcnt lgkmcnt(1)
	v_mfma_f32_16x16x32_bf16 v[102:105], v[220:223], v[196:199], v[102:105]
	v_mfma_f32_16x16x32_bf16 v[184:187], v[204:207], v[212:215], v[184:187]
	v_mfma_f32_16x16x32_bf16 v[188:191], v[220:223], v[212:215], v[188:191]
	v_mfma_f32_16x16x32_bf16 v[192:195], v[208:211], v[200:203], v[192:195]
	s_waitcnt lgkmcnt(0)
	v_mfma_f32_16x16x32_bf16 v[102:105], v[224:227], v[200:203], v[102:105]
	v_mfma_f32_16x16x32_bf16 v[184:187], v[208:211], v[216:219], v[184:187]
	v_mfma_f32_16x16x32_bf16 v[188:191], v[224:227], v[216:219], v[188:191]
	v_cvt_pk_bf16_f32 v102, v102, v103
	v_cvt_pk_bf16_f32 v103, v104, v105
	s_nop 5
	v_add_u32_e32 v104, s10, v128
	ds_write_b64 v104, v[102:103]
	v_add_u32_e32 v104, s14, v156
	v_add_u32_e32 v179, s14, v128
	v_cvt_pk_bf16_f32 v102, v184, v185
	v_cvt_pk_bf16_f32 v103, v186, v187
	ds_write_b64 v104, v[102:103]
	v_add_u32_e32 v104, s10, v156
	v_cvt_pk_bf16_f32 v174, v192, v193
	v_cvt_pk_bf16_f32 v175, v194, v195
	ds_write_b64 v179, v[174:175]
	v_cvt_pk_bf16_f32 v102, v188, v189
	v_cvt_pk_bf16_f32 v103, v190, v191
	ds_write_b64 v104, v[102:103]
	ds_read_b128 v[102:105], v131
	ds_read_b128 v[184:187], v130
	ds_read_b128 v[188:191], v131 offset:64
	s_add_i32 s11, s11, 64
	s_sub_i32 s19, s19, 64
	s_waitcnt lgkmcnt(2)
	v_pk_mul_f32 v[174:175], v[168:169], v[104:105]
	v_pk_mul_f32 v[192:193], v[166:167], v[102:103]
	ds_read_b128 v[166:169], v130 offset:64
	v_pk_mul_f32 v[2:3], v[2:3], v[104:105]
	v_pk_mul_f32 v[0:1], v[0:1], v[102:103]
	s_waitcnt lgkmcnt(2)
	v_pk_fma_f32 v[70:71], v[70:71], v[186:187], v[2:3]
	v_pk_fma_f32 v[68:69], v[68:69], v[184:185], v[0:1]
	s_waitcnt lgkmcnt(1)
	v_pk_mul_f32 v[0:1], v[92:93], v[190:191]
	v_pk_mul_f32 v[2:3], v[90:91], v[188:189]
	s_waitcnt lgkmcnt(0)
	v_pk_fma_f32 v[74:75], v[74:75], v[168:169], v[0:1]
	v_pk_fma_f32 v[72:73], v[72:73], v[166:167], v[2:3]
	v_pk_mul_f32 v[0:1], v[96:97], v[190:191]
	v_pk_mul_f32 v[2:3], v[94:95], v[188:189]
	v_pk_mul_f32 v[172:173], v[172:173], v[104:105]
	v_pk_mul_f32 v[170:171], v[170:171], v[102:103]
	v_pk_fma_f32 v[78:79], v[78:79], v[168:169], v[0:1]
	v_pk_fma_f32 v[76:77], v[76:77], v[166:167], v[2:3]
	v_pk_mul_f32 v[0:1], v[100:101], v[190:191]
	v_pk_mul_f32 v[2:3], v[98:99], v[188:189]
	v_pk_fma_f32 v[62:63], v[62:63], v[186:187], v[172:173]
	v_pk_fma_f32 v[60:61], v[60:61], v[184:185], v[170:171]
	v_pk_mul_f32 v[170:171], v[182:183], v[104:105]
	v_pk_mul_f32 v[172:173], v[180:181], v[102:103]
	v_pk_fma_f32 v[82:83], v[82:83], v[168:169], v[0:1]
	v_pk_fma_f32 v[80:81], v[80:81], v[166:167], v[2:3]
	v_pk_mul_f32 v[0:1], v[6:7], v[190:191]
	v_pk_mul_f32 v[2:3], v[4:5], v[188:189]
	v_pk_fma_f32 v[58:59], v[58:59], v[186:187], v[174:175]
	v_pk_fma_f32 v[56:57], v[56:57], v[184:185], v[192:193]
	v_pk_fma_f32 v[66:67], v[66:67], v[186:187], v[170:171]
	v_pk_fma_f32 v[64:65], v[64:65], v[184:185], v[172:173]
	v_pk_fma_f32 v[86:87], v[86:87], v[168:169], v[0:1]
	s_cmp_lg_u32 s78, s17
	v_pk_fma_f32 v[84:85], v[84:85], v[166:167], v[2:3]
	s_cbranch_scc0 .LBB0_149

; #define LAS __attribute__((address_space(3)))
; __device__ __forceinline__ unsigned cvt_pk_bf16(float lo, float hi) { unsigned r; asm("v_cvt_pk_bf16_f32 %0, %1, %2" : "=v"(r) : "v"(lo), "v"(hi)); return r; }
; __device__ __forceinline__ float bf_lo(unsigned u) { return __uint_as_float(u << 16); }
; __device__ __forceinline__ float bf_hi(unsigned u) { return __uint_as_float(u & 0xffff0000u); }
; __device__ __forceinline__ float rcp_(float x) { return __builtin_amdgcn_rcpf(x); }
; __device__ __forceinline__ float exp2_(float x) { return __builtin_amdgcn_exp2f(x); }
; template <int DK, bool IS_A, int NDV>
; __device__ __forceinline__ void mix_stream(const Params& p, LAS unsigned char* lds, int l, int rs, int T, int h, int dir, int dvh) {
;     ...
;                 float pre0 = 0.f, pre1 = 0.f, ref0 = 0.f, ref1 = 0.f, tot0 = 0.f, tot1 = 0.f;
; #pragma unroll
;                 for (int s8 = 0; s8 < 8; ++s8) { const f32x2 v = *(const LAS f32x2*)(seg + s8 * DK + 2 * cp);
;                     if (s8 < sg) { pre0 += v.x; pre1 += v.y; } if (s8 < 4) { ref0 += v.x; ref1 += v.y; } tot0 += v.x; tot1 += v.y; }
;                 f32x2 E = (f32x2){exp2_(fminf(fmaxf(pre0 - ref0, -115.f), 115.f)), exp2_(fminf(fmaxf(pre1 - ref1, -115.f), 115.f))};
; #pragma unroll
;                 for (int ip = 0; ip < 4; ++ip) { unsigned kp[2];
; #pragma unroll
;                     for (int e = 0; e < 2; ++e) { const int i = 2 * ip + e;
;                         const f32x2 f = (f32x2){exp2_(bf_lo(rf[par][i])), exp2_(bf_hi(rf[par][i]))};
;                         E = __builtin_elementwise_max(E * f, (f32x2){1e-35f, 1e-35f});
;                         const f32x2 r = (f32x2){rcp_(E.x), rcp_(E.y)};
;                         const f32x2 k = r - f * r;
;                         const f32x2 qv = (f32x2){bf_lo(rq[par][i]), bf_hi(rq[par][i])} * E;
;                         const int t = sg * 8 + i;
;                         const int cb4 = (4 * cp) ^ ((i >= 4 ? 16 : 0) ^ sgx);
;                         *(LAS unsigned*)(Qs + t * QP + cb4) = cvt_pk_bf16(qv.x, qv.y);
;                         kp[e] = cvt_pk_bf16(k.x, k.y);
;                         *(LAS unsigned*)(Ks + t * QP + cb4) = kp[e]; }
.LBB0_175:
	ds_read2st64_b64 v[0:3], v108 offset1:1
	v_exp_f32_e32 v104, v104
	v_exp_f32_e32 v105, v105
	v_exp_f32_e32 v102, v102
	v_exp_f32_e32 v103, v103
	s_waitcnt lgkmcnt(0)
	v_add_f32_e32 v0, 0, v0
	v_add_f32_e32 v1, 0, v1
	v_cndmask_b32_e64 v4, 0, v1, s[58:59]
	v_cndmask_b32_e64 v5, 0, v0, s[58:59]
	v_add_f32_e32 v6, v2, v5
	v_add_f32_e32 v7, v3, v4
	v_cndmask_b32_e64 v4, v4, v7, s[60:61]
	v_cndmask_b32_e64 v5, v5, v6, s[60:61]
	v_add_f32_e32 v6, v0, v2
	v_add_f32_e32 v7, v1, v3
	ds_read2st64_b64 v[0:3], v108 offset0:2 offset1:3
	v_exp_f32_e32 v100, v100
	v_exp_f32_e32 v101, v101
	v_exp_f32_e32 v98, v98
	v_exp_f32_e32 v99, v99
	s_waitcnt lgkmcnt(0)
	v_add_f32_e32 v166, v0, v5
	v_add_f32_e32 v167, v1, v4
	v_cndmask_b32_e64 v4, v4, v167, s[62:63]
	v_cndmask_b32_e64 v5, v5, v166, s[62:63]
	v_add_f32_e32 v0, v6, v0
	v_add_f32_e32 v1, v7, v1
	v_add_f32_e32 v6, v2, v5
	v_add_f32_e32 v7, v3, v4
	v_add_f32_e32 v167, v0, v2
	v_add_f32_e32 v166, v1, v3
	ds_read2st64_b64 v[0:3], v108 offset0:4 offset1:5
	v_cndmask_b32_e64 v4, v4, v7, s[64:65]
	v_cndmask_b32_e64 v5, v5, v6, s[64:65]
	v_exp_f32_e32 v96, v96
	v_exp_f32_e32 v97, v97
	s_waitcnt lgkmcnt(0)
	v_add_f32_e32 v6, v0, v5
	v_add_f32_e32 v7, v1, v4
	v_cndmask_b32_e64 v4, v4, v7, s[66:67]
	v_cndmask_b32_e64 v5, v5, v6, s[66:67]
	v_add_f32_e32 v6, v2, v5
	v_add_f32_e32 v7, v3, v4
	v_cndmask_b32_e64 v168, v4, v7, s[68:69]
	v_cndmask_b32_e64 v169, v5, v6, s[68:69]
	ds_read2st64_b64 v[4:7], v108 offset0:6 offset1:7
	v_add_u32_e32 v172, s9, v112
	v_exp_f32_e32 v94, v94
	v_exp_f32_e32 v95, v95
	v_exp_f32_e32 v92, v92
	s_waitcnt lgkmcnt(0)
	v_add_f32_e32 v170, v4, v169
	v_add_f32_e32 v171, v5, v168
	v_cndmask_b32_e64 v168, v168, v171, s[70:71]
	v_cndmask_b32_e64 v169, v169, v170, s[70:71]
	v_add_f32_e32 v170, v6, v169
	v_add_f32_e32 v171, v7, v168
	v_cndmask_b32_e64 v171, v168, v171, s[72:73]
	v_cndmask_b32_e64 v168, v169, v170, s[72:73]
	v_sub_f32_e32 v168, v168, v167
	v_sub_f32_e32 v169, v171, v166
	v_med3_f32 v168, v168, s2, v240
	v_med3_f32 v169, v169, s2, v240
	v_exp_f32_e32 v168, v168
	v_exp_f32_e32 v169, v169
	v_exp_f32_e32 v93, v93
	v_exp_f32_e32 v90, v90
	v_exp_f32_e32 v91, v91
	v_pk_mul_f32 v[168:169], v[104:105], v[168:169]
	s_andn2_b64 vcc, exec, s[0:1]
	v_max_f32_e32 v169, 0x554ad2e, v169
	v_max_f32_e32 v168, 0x554ad2e, v168
	v_rcp_f32_e32 v170, v168
	v_rcp_f32_e32 v171, v169
	s_nop 0
	v_pk_fma_f32 v[104:105], v[104:105], v[170:171], v[170:171] neg_lo:[1,0,0] neg_hi:[1,0,0]
	s_waitcnt vmcnt(0)
	v_lshlrev_b32_e32 v170, 16, v122
	v_and_b32_e32 v171, 0xffff0000, v122
	v_pk_mul_f32 v[170:171], v[168:169], v[170:171]
	v_pk_mul_f32 v[168:169], v[102:103], v[168:169]
	v_cvt_pk_bf16_f32 v170, v170, v171
	v_add_u32_e32 v171, s8, v112
	v_max_f32_e32 v169, 0x554ad2e, v169
	v_max_f32_e32 v168, 0x554ad2e, v168
	v_cvt_pk_bf16_f32 v104, v104, v105
	ds_write2st64_b32 v171, v170, v104 offset1:68
	v_rcp_f32_e32 v170, v168
	v_rcp_f32_e32 v171, v169
	s_nop 0
	v_pk_fma_f32 v[102:103], v[102:103], v[170:171], v[170:171] neg_lo:[1,0,0] neg_hi:[1,0,0]
	v_lshlrev_b32_e32 v170, 16, v124
	v_and_b32_e32 v171, 0xffff0000, v124
	v_pk_mul_f32 v[170:171], v[168:169], v[170:171]
	v_pk_mul_f32 v[168:169], v[100:101], v[168:169]
	v_cvt_pk_bf16_f32 v105, v170, v171
	v_cvt_pk_bf16_f32 v102, v102, v103
	s_nop 0
	v_max_f32_e32 v169, 0x554ad2e, v169
	v_max_f32_e32 v168, 0x554ad2e, v168
	v_rcp_f32_e32 v170, v168
	v_rcp_f32_e32 v171, v169
	s_nop 0
	v_pk_fma_f32 v[100:101], v[100:101], v[170:171], v[170:171] neg_lo:[1,0,0] neg_hi:[1,0,0]
	v_lshlrev_b32_e32 v170, 16, v129
	v_and_b32_e32 v171, 0xffff0000, v129
	v_pk_mul_f32 v[170:171], v[168:169], v[170:171]
	v_pk_mul_f32 v[168:169], v[98:99], v[168:169]
	v_cvt_pk_bf16_f32 v103, v170, v171
	v_cvt_pk_bf16_f32 v100, v100, v101
	v_add_u32_e32 v101, 0x4400, v172
	v_max_f32_e32 v169, 0x554ad2e, v169
	v_max_f32_e32 v168, 0x554ad2e, v168
	v_rcp_f32_e32 v170, v168
	v_rcp_f32_e32 v171, v169
	ds_write2_b32 v101, v102, v100 offset1:68
	ds_write2_b32 v172, v105, v103 offset1:68
	v_pk_fma_f32 v[98:99], v[98:99], v[170:171], v[170:171] neg_lo:[1,0,0] neg_hi:[1,0,0]
	v_lshlrev_b32_e32 v170, 16, v150
	v_and_b32_e32 v171, 0xffff0000, v150
	v_pk_mul_f32 v[170:171], v[168:169], v[170:171]
	v_pk_mul_f32 v[168:169], v[96:97], v[168:169]
	v_cvt_pk_bf16_f32 v101, v170, v171
	v_cvt_pk_bf16_f32 v98, v98, v99
	ds_write_b32 v172, v101 offset:544
	v_max_f32_e32 v169, 0x554ad2e, v169
	v_max_f32_e32 v168, 0x554ad2e, v168
	v_rcp_f32_e32 v170, v168
	v_rcp_f32_e32 v171, v169
	v_add_u32_e32 v101, 0x200, v133
	ds_write_b32 v172, v98 offset:17952
	v_pk_fma_f32 v[96:97], v[96:97], v[170:171], v[170:171] neg_lo:[1,0,0] neg_hi:[1,0,0]
	v_lshlrev_b32_e32 v170, 16, v153
	v_and_b32_e32 v171, 0xffff0000, v153
	v_pk_mul_f32 v[170:171], v[168:169], v[170:171]
	v_pk_mul_f32 v[168:169], v[94:95], v[168:169]
	v_cvt_pk_bf16_f32 v99, v170, v171
	v_cvt_pk_bf16_f32 v96, v96, v97
	s_nop 0
	v_max_f32_e32 v169, 0x554ad2e, v169
	v_max_f32_e32 v168, 0x554ad2e, v168
	v_rcp_f32_e32 v170, v168
	v_rcp_f32_e32 v171, v169
	s_nop 0
	v_pk_fma_f32 v[94:95], v[94:95], v[170:171], v[170:171] neg_lo:[1,0,0] neg_hi:[1,0,0]
	v_lshlrev_b32_e32 v170, 16, v157
	v_and_b32_e32 v171, 0xffff0000, v157
	v_pk_mul_f32 v[170:171], v[168:169], v[170:171]
	v_pk_mul_f32 v[168:169], v[92:93], v[168:169]
	v_cvt_pk_bf16_f32 v97, v170, v171
	v_cvt_pk_bf16_f32 v94, v94, v95
	v_add_u32_e32 v95, 0x4600, v133
	v_max_f32_e32 v169, 0x554ad2e, v169
	v_max_f32_e32 v168, 0x554ad2e, v168
	v_rcp_f32_e32 v170, v168
	v_rcp_f32_e32 v171, v169
	ds_write2_b32 v95, v96, v94 offset0:76 offset1:144
	ds_write2_b32 v101, v99, v97 offset0:76 offset1:144
	v_add_u32_e32 v97, 0x400, v133
	v_pk_fma_f32 v[92:93], v[92:93], v[170:171], v[170:171] neg_lo:[1,0,0] neg_hi:[1,0,0]
	v_lshlrev_b32_e32 v170, 16, v160
	v_and_b32_e32 v171, 0xffff0000, v160
	v_pk_mul_f32 v[170:171], v[168:169], v[170:171]
	v_pk_mul_f32 v[168:169], v[90:91], v[168:169]
	v_cvt_pk_bf16_f32 v95, v170, v171
	v_cvt_pk_bf16_f32 v92, v92, v93
	s_nop 0
	v_max_f32_e32 v169, 0x554ad2e, v169
	v_max_f32_e32 v168, 0x554ad2e, v168
	v_rcp_f32_e32 v170, v168
	v_rcp_f32_e32 v171, v169
	s_nop 0
	v_pk_fma_f32 v[90:91], v[90:91], v[170:171], v[170:171] neg_lo:[1,0,0] neg_hi:[1,0,0]
	v_lshlrev_b32_e32 v170, 16, v163
	v_and_b32_e32 v171, 0xffff0000, v163
	v_cvt_pk_bf16_f32 v90, v90, v91
	v_add_u32_e32 v91, 0x4800, v133
	v_pk_mul_f32 v[168:169], v[168:169], v[170:171]
	ds_write2_b32 v91, v92, v90 offset0:84 offset1:152
	v_cvt_pk_bf16_f32 v93, v168, v169
	ds_write2_b32 v97, v95, v93 offset0:84 offset1:152
	s_cbranch_vccnz .LBB0_177
; template <int DK, bool IS_A, int NDV>
; __device__ __forceinline__ void mix_stream(const Params& p, LAS unsigned char* lds, int l, int rs, int T, int h, int dir, int dvh) {
;     ...
;                     kt0[ip] = __builtin_amdgcn_perm(kp[1], kp[0], 0x05040100u); kt1[ip] = __builtin_amdgcn_perm(kp[1], kp[0], 0x07060302u);
;                     vt0[ip] = __builtin_amdgcn_perm(rv[par][2 * ip + 1], rv[par][2 * ip], 0x05040100u); vt1[ip] = __builtin_amdgcn_perm(rv[par][2 * ip + 1], rv[par][2 * ip], 0x07060302u);
;                 }
;                 if (sg == 0) { *(LAS f32x2*)(cdec + 2 * cp) = (f32x2){exp2_(fmaxf(tot0, -115.f)), exp2_(fmaxf(tot1, -115.f))};
;                                *(LAS f32x2*)(csc + 2 * cp) = (f32x2){exp2_(fmaxf(tot0 - ref0, -115.f)), exp2_(fmaxf(tot1 - ref1, -115.f))}; }
;                 *(LAS u32x4*)(Kt + (2 * cp) * TP + ((sg * 16) ^ (gk << 4))) = (u32x4){kt0[0], kt0[1], kt0[2], kt0[3]};
;                 *(LAS u32x4*)(Kt + (2 * cp + 1) * TP + ((sg * 16) ^ (gk << 4))) = (u32x4){kt1[0], kt1[1], kt1[2], kt1[3]};
;             } else {
;                 const int ci = cp & 31;
; #pragma unroll
;                 for (int ip = 0; ip < 4; ++ip) { unsigned kp[2];
; #pragma unroll
;                     for (int e = 0; e < 2; ++e) { const int i = 2 * ip + e; const int t = sg * 8 + i;
;                         const float dd = (float)(t - 31) * lg;
;                         const float sc = __expf(cp < 32 ? dd : -dd);
;                         kp[e] = cvt_pk_bf16(bf_lo(rq[par][i]) * sc, bf_hi(rq[par][i]) * sc);
;                         *(LAS unsigned*)((cp < 32 ? Qs : Ks) + t * QP + ((4 * ci) ^ ((i >= 4 ? 16 : 0) ^ sgx))) = kp[e]; }
;                     kt0[ip] = __builtin_amdgcn_perm(kp[1], kp[0], 0x05040100u); kt1[ip] = __builtin_amdgcn_perm(kp[1], kp[0], 0x07060302u);
;                     vt0[ip] = __builtin_amdgcn_perm(rv[par][2 * ip + 1], rv[par][2 * ip], 0x05040100u); vt1[ip] = __builtin_amdgcn_perm(rv[par][2 * ip + 1], rv[par][2 * ip], 0x07060302u);
;                 }
;                 if (cp >= 32) { *(LAS u32x4*)(Kt + (2 * ci) * TP + ((sg * 16) ^ (gk << 4))) = (u32x4){kt0[0], kt0[1], kt0[2], kt0[3]};
;                                 *(LAS u32x4*)(Kt + (2 * ci + 1) * TP + ((sg * 16) ^ (gk << 4))) = (u32x4){kt1[0], kt1[1], kt1[2], kt1[3]}; }
;             }
;             if (NDV == 8 || cp < 32) {
	v_add_f32_e32 v1, v166, v1
	v_add_f32_e32 v0, v167, v0
	v_add_f32_e32 v1, v1, v3
	v_add_f32_e32 v0, v0, v2
	v_add_f32_e32 v1, v1, v5
	v_add_f32_e32 v0, v0, v4
	v_add_f32_e32 v3, v1, v7
	v_add_f32_e32 v2, v0, v6
	v_max_f32_e32 v0, 0xc2e60000, v2
	v_max_f32_e32 v1, 0xc2e60000, v3
	v_sub_f32_e32 v2, v2, v167
	v_sub_f32_e32 v3, v3, v166
	v_exp_f32_e32 v0, v0
	v_exp_f32_e32 v1, v1
	v_max_f32_e32 v2, 0xc2e60000, v2
	v_max_f32_e32 v3, 0xc2e60000, v3
	v_exp_f32_e32 v2, v2
	v_exp_f32_e32 v3, v3
	ds_write_b64 v109, v[0:1]
	ds_write_b64 v110, v[2:3]
	v_max_f32_e32 v4, 0xc2e60000, v167
	v_max_f32_e32 v5, 0xc2e60000, v166
	v_exp_f32_e32 v4, v4
	v_exp_f32_e32 v5, v5
	s_nop 0
	ds_write_b64 v109, v[4:5] offset:18432
.LBB0_177:
	v_perm_b32 v0, v102, v104, s3
	v_perm_b32 v1, v98, v100, s3
	v_perm_b32 v2, v94, v96, s3
	v_perm_b32 v3, v90, v92, s3
	v_perm_b32 v4, v102, v104, s23
	v_perm_b32 v102, v127, v123, s3
	v_perm_b32 v166, v127, v123, s23
	v_perm_b32 v5, v98, v100, s23
	v_perm_b32 v103, v152, v149, s3
	v_perm_b32 v167, v152, v149, s23
	v_perm_b32 v6, v94, v96, s23
	v_perm_b32 v104, v159, v155, s3
	v_perm_b32 v168, v159, v155, s23
	v_perm_b32 v7, v90, v92, s23
	v_perm_b32 v105, v165, v162, s3
	v_perm_b32 v169, v165, v162, s23
	ds_write_b128 v134, v[0:3] offset:53248
	ds_write_b128 v134, v[4:7] offset:53392
	ds_write_b128 v134, v[102:105] offset:34816
	ds_write_b128 v134, v[166:169] offset:34960
	s_add_i32 s17, s17, 1
	s_cmp_ge_u32 s17, s78
	s_cbranch_scc1 .LBB0_172
	s_add_i32 s77, s11, 0x80
	s_add_i32 vcc_lo, s19, 0xffffff80
	s_and_b64 s[12:13], s[40:41], exec
	s_cselect_b32 s12, s77, vcc_lo
	s_add_i32 s12, s12, s18
	s_mul_hi_i32 s13, s12, 0x5000
	s_mulk_i32 s12, 0x5000
	s_add_u32 s12, s98, s12
	s_addc_u32 s13, s99, s13
	global_load_dword v122, v176, s[12:13]
	global_load_dword v119, v8, s[12:13]
	global_load_dword v123, v10, s[12:13]
	global_load_dword v124, v12, s[12:13]
	global_load_dword v125, v14, s[12:13]
	global_load_dword v127, v16, s[12:13]
	global_load_dword v129, v18, s[12:13]
	global_load_dword v147, v20, s[12:13]
	global_load_dword v149, v22, s[12:13]
	global_load_dword v150, v24, s[12:13]
	global_load_dword v151, v26, s[12:13]
	global_load_dword v152, v28, s[12:13]
	global_load_dword v153, v30, s[12:13]
	global_load_dword v154, v32, s[12:13]
	global_load_dword v155, v34, s[12:13]
	global_load_dword v157, v36, s[12:13]
	global_load_dword v158, v38, s[12:13]
	global_load_dword v159, v40, s[12:13]
	global_load_dword v160, v42, s[12:13]
	global_load_dword v161, v44, s[12:13]
	global_load_dword v162, v48, s[12:13]
	global_load_dword v163, v50, s[12:13]
	global_load_dword v164, v52, s[12:13]
	global_load_dword v165, v54, s[12:13]
	s_branch .LBB0_172
